# v34_seam_order
# speedup vs baseline: 1.0085x; 1.0085x over previous
; DI void g5_phase(const Params& p, int L) {
;     ...
;   for (int t = blockIdx.x; t < nM * 4; t += gridDim.x) {
;     int pm, pn; tile_coords(t, 4, pm, pn);
;     gemm_tile<E_ST_MX, 512, 512>(p, L, (const u16*)(R + R_OA), wl + WO_WA, pm, pn);
;     gemm_tile<E_GATE_A, 1024, 1024>(p, L, Ybf, wl + WO_WGA, pm, pn);
;     gemm_tile<E_ST_GT, 512, 512>(p, L, (const u16*)(R + R_OB), wl + WO_WB, pm, pn);
;     gemm_tile<E_GATE_B, 1024, 1024>(p, L, Ybf, wl + WO_WGB, pm, pn);
;   }
.Lg5pub_done:
	s_or_b64 exec, exec, s[4:5]
	v_readlane_b32 s4, v254, 3
	v_readlane_b32 s100, v254, 0
	s_nop 3
	s_cmp_lt_u32 s100, 8
	s_cbranch_scc0 .Lg5_norm
	s_cmp_lt_u32 s62, 0x100
	s_cbranch_scc0 .Lg5_sp2
	s_add_i32 s62, s62, 0x200
	s_branch .Lg5_cont
.Lg5_sp2:
	s_cmp_ge_u32 s62, 0x200
	s_cbranch_scc0 .Lg5_exit
	s_sub_i32 s62, s62, 0x100
.Lg5_cont:
	s_cmp_eq_u32 s100, s100
	s_branch .Lg5_latch_tail
.Lg5_exit:
	s_mov_b32 s62, 0x300
	s_cmp_lg_u32 s100, s100
	s_branch .Lg5_latch_tail
.Lg5_norm:
	s_add_i32 s62, s62, s4
	s_cmpk_lt_i32 s62, 0x208
.Lg5_latch_tail:
	v_readlane_b32 s50, v254, 47
	v_readlane_b32 s5, v254, 4
	s_cbranch_scc1 .LBB0_1728
	v_readlane_b32 s68, v254, 25
	v_readlane_b32 s69, v254, 26
	v_readlane_b32 s70, v254, 27
	v_readlane_b32 s71, v254, 28
	s_mov_b32 s77, 0x2aaaaaab
	s_movk_i32 s66, 0x84
	s_movk_i32 s67, 0x1dff
	s_movk_i32 s76, 0x1e7f
